# NSA selected branch: K-fragment LDS reads hoisted to the top of the key-block iteration, ahead of next_valid and the next tile's global loads
# baseline (speedup 1.0000x reference)
; DI void nsa_item(const Params& p, int bk, int qb, char* smem, float Mb) {
;     ...
;         auto next_valid = [&](int j, unsigned long long& mout) {
;             for (; j <= cur; ++j) {
;                 if (j == 0 || j >= cur - 1) { mout = ~0ull; break; }
;                 const unsigned long long mm = masks[j];
;                 const unsigned mlo = __builtin_amdgcn_readfirstlane((unsigned)mm), mhi = __builtin_amdgcn_readfirstlane((unsigned)(mm >> 32));
;                 mout = ((unsigned long long)mhi << 32) | mlo;
;                 if (mout) break;
;             }
;             return j;
;         };
;     ...
;                 const char* kb_ = tb + bsel * 18432 + fr * 144 + fq * 16;
;                 bf16x8 kf[4][2], vf[4][2];
; #pragma unroll
;                 for (int k4 = 0; k4 < 4; ++k4) {
;                     kf[k4][0] = *(const bf16x8*)(kb_ + k4 * 16 * 144); kf[k4][1] = *(const bf16x8*)(kb_ + k4 * 16 * 144 + 64);
;                     vf[k4][0] = *(const bf16x8*)(kb_ + 9216 + k4 * 16 * 144); vf[k4][1] = *(const bf16x8*)(kb_ + 9216 + k4 * 16 * 144 + 64);
.LBB0_535:
	s_mul_i32 s6, s22, 0x4800
	v_add_u32_e32 v116, s6, v239
	ds_read_b128 v[120:123], v116
	ds_read_b128 v[128:131], v116 offset:64
	ds_read_b128 v[132:135], v116 offset:2304
	ds_read_b128 v[136:139], v116 offset:2368
	ds_read_b128 v[144:147], v116 offset:4608
	ds_read_b128 v[148:151], v116 offset:4672
	ds_read_b128 v[152:155], v116 offset:6912
	v_add_u32_e32 v242, 1, v245
	v_cmp_lt_i32_e64 s[4:5], v245, v238
	s_and_saveexec_b64 s[8:9], s[4:5]
	s_cbranch_execz .LBB0_546
	v_cmp_ne_u32_e64 s[4:5], 0, v242
	v_cmp_lt_i32_e64 s[6:7], v242, v197
	s_and_b64 s[4:5], s[4:5], s[6:7]
	v_mov_b64_e32 v[208:209], -1
	s_and_saveexec_b64 s[12:13], s[4:5]
	s_cbranch_execz .LBB0_545
	v_readlane_b32 s2, v249, 29
	v_add_u32_e32 v75, 2, v245
	s_mov_b64 s[16:17], 0
	v_lshl_add_u32 v74, v245, 3, s2
	s_or_b64 s[18:19], s[18:19], exec
	v_mov_b32_e32 v242, v75
	s_mov_b64 s[4:5], -1
	v_readfirstlane_b32 s21, v73
	v_readfirstlane_b32 s20, v72
	s_cmp_lg_u64 s[20:21], 0
	s_cbranch_scc1 .LBB0_538
	v_cmp_eq_u32_e64 s[4:5], 0, v242
	v_cmp_ge_i32_e64 s[6:7], v242, v197
	s_or_b64 s[6:7], s[4:5], s[6:7]
	s_andn2_b64 s[18:19], s[18:19], exec
	s_and_b64 s[6:7], s[6:7], exec
	v_add_u32_e32 v75, 1, v242
	v_add_u32_e32 v74, 8, v74
	s_mov_b64 s[4:5], 0
	s_or_b64 s[18:19], s[18:19], s[6:7]
	s_branch .LBB0_539

; DI void nsa_item(const Params& p, int bk, int qb, char* smem, float Mb) {
;     ...
;             const int jn = next_valid(j + 1, mn);
;             gload(jn <= cur ? jn : j);
;             const unsigned sub = (unsigned)(m >> (wave * 16)) & 0xffffu;
;             if (sub) {
;                 const char* kb_ = tb + bsel * 18432 + fr * 144 + fq * 16;
;                 bf16x8 kf[4][2], vf[4][2];
; #pragma unroll
;                 for (int k4 = 0; k4 < 4; ++k4) {
;                     kf[k4][0] = *(const bf16x8*)(kb_ + k4 * 16 * 144); kf[k4][1] = *(const bf16x8*)(kb_ + k4 * 16 * 144 + 64);
;                     vf[k4][0] = *(const bf16x8*)(kb_ + 9216 + k4 * 16 * 144); vf[k4][1] = *(const bf16x8*)(kb_ + 9216 + k4 * 16 * 144 + 64);
;                 }
;                 const bool mine = (sub >> fr) & 1u;
;                 const float Ml = mine ? Mb : 3.0e38f;
;                 const bool diag = (j == cur);
; #pragma unroll
;                 for (int g = 0; g < 3; ++g) {
;                     f32x4 st[4];
;                     st_from(kf, qf[g], st, -Ml);
.LBB0_546:
	s_or_b64 exec, exec, s[8:9]
	v_cmp_gt_i32_e64 s[4:5], v242, v238
	v_mov_b32_e32 v207, v189
	v_mov_b32_e32 v205, v189
	v_cndmask_b32_e64 v72, v242, v245, s[4:5]
	v_lshlrev_b32_e32 v72, 13, v72
	v_add3_u32 v254, v72, v188, v204
	v_add3_u32 v255, v72, v206, v204
	global_load_dwordx4 v[72:75], v254, s[50:51]
	global_load_dwordx4 v[76:79], v255, s[50:51]
	global_load_dwordx4 v[80:83], v254, s[36:37]
	global_load_dwordx4 v[84:87], v255, s[36:37]
	v_lshrrev_b64 v[88:89], s93, v[88:89]
	v_cmp_ne_u32_sdwa s[6:7], v88, v189 src0_sel:WORD_0 src1_sel:DWORD
	s_and_saveexec_b64 s[12:13], s[6:7]
	s_cbranch_execz .LBB0_534
	v_and_b32_e32 v88, v240, v88
	v_cmp_ne_u32_e64 s[6:7], 0, v88
	s_nop 1
	v_cndmask_b32_e64 v124, v229, v235, s[6:7]
	v_mov_b32_e32 v125, v124
	v_mov_b32_e32 v126, v124
	v_mov_b32_e32 v127, v124
	v_cmp_ne_u32_e64 s[6:7], v245, v238
	s_nop 3
	s_and_b64 s[8:9], exec, s[6:7]
	s_cbranch_scc1 .Lsel_fast
	s_waitcnt lgkmcnt(4)
	v_mfma_f32_16x16x32_bf16 v[92:95], v[132:135], v[0:3], v[124:127]
	v_mfma_f32_16x16x32_bf16 v[88:91], v[120:123], v[0:3], v[124:127]
	s_waitcnt lgkmcnt(3)
	v_mfma_f32_16x16x32_bf16 v[176:179], v[136:139], v[4:7], v[92:95]
	s_waitcnt lgkmcnt(2)
	v_mfma_f32_16x16x32_bf16 v[92:95], v[144:147], v[0:3], v[124:127]
	v_mfma_f32_16x16x32_bf16 v[184:187], v[128:131], v[4:7], v[88:91]
	ds_read_b128 v[108:111], v116 offset:9216
	s_nop 1
	ds_read_b128 v[88:91], v116 offset:9280
	ds_read_b128 v[140:143], v116 offset:6976
	s_waitcnt lgkmcnt(3)
	v_mfma_f32_16x16x32_bf16 v[156:159], v[152:155], v[0:3], v[124:127]
	v_mfma_f32_16x16x32_bf16 v[168:171], v[148:151], v[4:7], v[92:95]
	s_nop 2
	ds_read_b128 v[92:95], v116 offset:11520
	ds_read_b128 v[96:99], v116 offset:11584
	ds_read_b128 v[100:103], v116 offset:13824
	ds_read_b128 v[104:107], v116 offset:13888
	ds_read_b128 v[112:115], v116 offset:16128
	ds_read_b128 v[116:119], v116 offset:16192
	s_waitcnt lgkmcnt(6)
	v_mfma_f32_16x16x32_bf16 v[160:163], v[140:143], v[4:7], v[156:159]
	s_and_saveexec_b64 s[8:9], s[6:7]
	s_xor_b64 s[8:9], exec, s[8:9]
	s_cbranch_execz .LBB0_549
	v_exp_f32_e32 v156, v184
	v_exp_f32_e32 v157, v185
	v_exp_f32_e32 v158, v186
	v_exp_f32_e32 v159, v187
	v_exp_f32_e32 v164, v176
	v_exp_f32_e32 v165, v177
	v_exp_f32_e32 v166, v178
	v_exp_f32_e32 v167, v179
	v_exp_f32_e32 v172, v168
	v_exp_f32_e32 v173, v169
	v_exp_f32_e32 v174, v170
	v_exp_f32_e32 v175, v171
	v_exp_f32_e32 v180, v160
	v_exp_f32_e32 v181, v161
	v_exp_f32_e32 v182, v162
	v_exp_f32_e32 v183, v163
	v_pk_add_f32 v[184:185], v[156:157], v[158:159]
	v_pk_add_f32 v[186:187], v[164:165], v[166:167]
	v_pk_add_f32 v[176:177], v[172:173], v[174:175]
	v_pk_add_f32 v[178:179], v[180:181], v[182:183]
	v_pk_add_f32 v[184:185], v[184:185], v[186:187]
	v_pk_add_f32 v[176:177], v[176:177], v[178:179]
	v_pk_add_f32 v[184:185], v[184:185], v[176:177]
	v_add_f32_e32 v244, v244, v184
	v_add_f32_e32 v244, v244, v185
